# P8 out-projection epilogue: graduated vmcnt(12) waits on the first batch of 16 residual loads instead of vmcnt(0)
# speedup vs baseline: 1.0068x; 1.0068x over previous
.LBB0_767:
	s_lshl_b32 s0, s59, 8
	v_mov_b32_e32 v128, v212
	v_mov_b32_e32 v218, v213
	s_add_i32 s0, s0, s49
	v_and_b32_e32 v240, 64, v181
	v_add_u32_e32 v198, s0, v128
	s_lshl_b32 s0, s3, 8
	s_or_b32 s0, s0, s50
	v_lshl_add_u32 v194, v218, 3, s0
	v_ashrrev_i32_e32 v195, 31, v194
	v_lshlrev_b64 v[236:237], 2, v[194:195]
	v_ashrrev_i32_e32 v199, 31, v198
	v_lshl_add_u64 v[196:197], s[36:37], 0, v[236:237]
	v_lshlrev_b64 v[238:239], 12, v[198:199]
	v_lshl_add_u64 v[128:129], v[196:197], 0, v[238:239]
	global_load_dwordx4 v[220:223], v[128:129], off
	global_load_dwordx4 v[224:227], v[128:129], off offset:16
	global_load_dwordx4 v[228:231], v[128:129], off offset:512
	global_load_dwordx4 v[232:235], v[128:129], off offset:528
	v_add_u32_e32 v208, 16, v198
	v_add_u32_e32 v204, 32, v198
	v_add_u32_e32 v200, 48, v198
	v_ashrrev_i32_e32 v209, 31, v208
	v_ashrrev_i32_e32 v205, 31, v204
	v_ashrrev_i32_e32 v201, 31, v200
	v_lshlrev_b64 v[210:211], 12, v[208:209]
	v_lshlrev_b64 v[206:207], 12, v[204:205]
	v_lshlrev_b64 v[202:203], 12, v[200:201]
	v_lshl_add_u64 v[128:129], v[196:197], 0, v[210:211]
	v_lshl_add_u64 v[130:131], v[196:197], 0, v[206:207]
	v_lshl_add_u64 v[132:133], v[196:197], 0, v[202:203]
	global_load_dwordx4 v[168:171], v[128:129], off offset:16
	global_load_dwordx4 v[172:175], v[128:129], off
	global_load_dwordx4 v[160:163], v[128:129], off offset:528
	global_load_dwordx4 v[164:167], v[128:129], off offset:512
	global_load_dwordx4 v[152:155], v[130:131], off offset:16
	global_load_dwordx4 v[156:159], v[130:131], off
	global_load_dwordx4 v[144:147], v[130:131], off offset:528
	global_load_dwordx4 v[148:151], v[130:131], off offset:512
	global_load_dwordx4 v[136:139], v[132:133], off offset:16
	global_load_dwordx4 v[140:143], v[132:133], off
	s_nop 0
	global_load_dwordx4 v[128:131], v[132:133], off offset:528
	s_nop 0
	global_load_dwordx4 v[132:135], v[132:133], off offset:512
	v_xor_b32_e32 v219, 16, v181
	v_add_u32_e32 v240, 64, v240
	v_cmp_lt_i32_e64 s[0:1], v219, v240
	v_cmp_eq_u32_e32 vcc, 0, v218
	v_xor_b32_e32 v241, 32, v181
	v_cndmask_b32_e64 v218, v181, v219, s[0:1]
	v_lshlrev_b32_e32 v218, 2, v218
	v_cmp_lt_i32_e64 s[0:1], v241, v240
	s_waitcnt vmcnt(12)
	v_pk_add_f32 v[220:221], v[124:125], v[220:221]
	v_pk_add_f32 v[120:121], v[120:121], v[224:225]
	v_pk_add_f32 v[116:117], v[116:117], v[228:229]
	v_pk_add_f32 v[224:225], v[112:113], v[232:233]
	v_mul_f32_e32 v112, v221, v221
	v_mul_f32_e32 v113, v117, v117
	v_pk_add_f32 v[222:223], v[126:127], v[222:223]
	v_pk_add_f32 v[118:119], v[118:119], v[230:231]
	v_fmac_f32_e32 v112, v220, v220
	v_fmac_f32_e32 v113, v116, v116
	v_fmac_f32_e32 v112, v222, v222
	v_fmac_f32_e32 v113, v118, v118
	v_fmac_f32_e32 v112, v223, v223
	v_fmac_f32_e32 v113, v119, v119
	v_fmac_f32_e32 v112, v120, v120
	v_fmac_f32_e32 v113, v224, v224
	v_pk_add_f32 v[122:123], v[122:123], v[226:227]
	v_pk_add_f32 v[226:227], v[114:115], v[234:235]
	v_fmac_f32_e32 v112, v121, v121
	v_fmac_f32_e32 v113, v225, v225
	v_fmac_f32_e32 v112, v122, v122
	v_fmac_f32_e32 v113, v226, v226
	v_fmac_f32_e32 v112, v123, v123
	v_fmac_f32_e32 v113, v227, v227
	v_add_f32_e32 v124, v112, v113
	ds_bpermute_b32 v125, v218, v124
	v_cndmask_b32_e64 v112, v181, v241, s[0:1]
	v_lshlrev_b32_e32 v126, 2, v112
	v_lshl_add_u64 v[112:113], s[30:31], 0, v[238:239]
	v_lshl_add_u64 v[114:115], v[112:113], 0, v[236:237]
	s_waitcnt lgkmcnt(0)
	v_add_f32_e32 v112, v124, v125
	ds_bpermute_b32 v113, v126, v112
	global_store_dwordx4 v[114:115], v[220:223], off
	global_store_dwordx4 v[114:115], v[120:123], off offset:16
	global_store_dwordx4 v[114:115], v[116:119], off offset:512
	global_store_dwordx4 v[114:115], v[224:227], off offset:528
	s_and_saveexec_b64 s[0:1], vcc
	s_cbranch_execz .LBB0_769
	s_waitcnt lgkmcnt(0)
	v_add_f32_e32 v114, v112, v113
	v_lshl_add_u64 v[112:113], v[198:199], 2, s[38:39]
	global_atomic_add_f32 v[112:113], v114, off
.LBB0_769:
	s_or_b64 exec, exec, s[0:1]
	s_waitcnt vmcnt(12)
	v_pk_add_f32 v[108:109], v[108:109], v[172:173]
	v_pk_add_f32 v[100:101], v[100:101], v[164:165]
	v_mul_f32_e32 v116, v109, v109
	s_waitcnt lgkmcnt(0)
	v_pk_add_f32 v[112:113], v[96:97], v[160:161]
	v_mul_f32_e32 v96, v101, v101
	v_pk_add_f32 v[110:111], v[110:111], v[174:175]
	v_fmac_f32_e32 v116, v108, v108
	v_pk_add_f32 v[102:103], v[102:103], v[166:167]
	v_fmac_f32_e32 v96, v100, v100
	v_fmac_f32_e32 v116, v110, v110
	v_fmac_f32_e32 v96, v102, v102
	v_pk_add_f32 v[104:105], v[104:105], v[168:169]
	v_fmac_f32_e32 v116, v111, v111
	v_fmac_f32_e32 v96, v103, v103
	v_fmac_f32_e32 v116, v104, v104
	v_fmac_f32_e32 v96, v112, v112
	v_pk_add_f32 v[106:107], v[106:107], v[170:171]
	v_fmac_f32_e32 v116, v105, v105
	v_pk_add_f32 v[114:115], v[98:99], v[162:163]
	v_fmac_f32_e32 v96, v113, v113
	v_fmac_f32_e32 v116, v106, v106
	v_fmac_f32_e32 v96, v114, v114
	v_fmac_f32_e32 v116, v107, v107
	v_fmac_f32_e32 v96, v115, v115
	v_add_f32_e32 v116, v116, v96
	ds_bpermute_b32 v117, v218, v116
	v_lshl_add_u64 v[96:97], s[30:31], 0, v[210:211]
	v_lshl_add_u64 v[98:99], v[194:195], 2, v[96:97]
	global_store_dwordx4 v[98:99], v[108:111], off
	global_store_dwordx4 v[98:99], v[104:107], off offset:16
	global_store_dwordx4 v[98:99], v[100:103], off offset:512
	global_store_dwordx4 v[98:99], v[112:115], off offset:528
	s_waitcnt lgkmcnt(0)
	v_add_f32_e32 v96, v116, v117
	ds_bpermute_b32 v97, v126, v96
	s_and_saveexec_b64 s[0:1], vcc
	s_cbranch_execz .LBB0_771
	s_waitcnt lgkmcnt(0)
	v_add_f32_e32 v98, v96, v97
	v_lshl_add_u64 v[96:97], v[208:209], 2, s[38:39]
	global_atomic_add_f32 v[96:97], v98, off
.LBB0_771:
	s_or_b64 exec, exec, s[0:1]
	s_waitcnt vmcnt(12)
	v_pk_add_f32 v[92:93], v[92:93], v[156:157]
	v_pk_add_f32 v[84:85], v[84:85], v[148:149]
	v_mul_f32_e32 v100, v93, v93
	s_waitcnt lgkmcnt(0)
	v_pk_add_f32 v[96:97], v[80:81], v[144:145]
	v_mul_f32_e32 v80, v85, v85
	v_pk_add_f32 v[94:95], v[94:95], v[158:159]
	v_fmac_f32_e32 v100, v92, v92
	v_pk_add_f32 v[86:87], v[86:87], v[150:151]
	v_fmac_f32_e32 v80, v84, v84
	v_fmac_f32_e32 v100, v94, v94
	v_fmac_f32_e32 v80, v86, v86
	v_pk_add_f32 v[88:89], v[88:89], v[152:153]
	v_fmac_f32_e32 v100, v95, v95
	v_fmac_f32_e32 v80, v87, v87
	v_fmac_f32_e32 v100, v88, v88
	v_fmac_f32_e32 v80, v96, v96
	v_pk_add_f32 v[90:91], v[90:91], v[154:155]
	v_fmac_f32_e32 v100, v89, v89
	v_pk_add_f32 v[98:99], v[82:83], v[146:147]
	v_fmac_f32_e32 v80, v97, v97
	v_fmac_f32_e32 v100, v90, v90
	v_fmac_f32_e32 v80, v98, v98
	v_fmac_f32_e32 v100, v91, v91
	v_fmac_f32_e32 v80, v99, v99
	v_add_f32_e32 v100, v100, v80
	ds_bpermute_b32 v101, v218, v100
	v_lshl_add_u64 v[80:81], s[30:31], 0, v[206:207]
	v_lshl_add_u64 v[82:83], v[194:195], 2, v[80:81]
	global_store_dwordx4 v[82:83], v[92:95], off
	global_store_dwordx4 v[82:83], v[88:91], off offset:16
	global_store_dwordx4 v[82:83], v[84:87], off offset:512
	global_store_dwordx4 v[82:83], v[96:99], off offset:528
	s_waitcnt lgkmcnt(0)
	v_add_f32_e32 v80, v100, v101
	ds_bpermute_b32 v81, v126, v80
	s_and_saveexec_b64 s[0:1], vcc
	s_cbranch_execz .LBB0_773
	s_waitcnt lgkmcnt(0)
	v_add_f32_e32 v82, v80, v81
	v_lshl_add_u64 v[80:81], v[204:205], 2, s[38:39]
	global_atomic_add_f32 v[80:81], v82, off
.LBB0_773:
	s_or_b64 exec, exec, s[0:1]
	s_waitcnt vmcnt(12)
	v_pk_add_f32 v[76:77], v[76:77], v[140:141]
	v_pk_add_f32 v[68:69], v[68:69], v[132:133]
	v_mul_f32_e32 v84, v77, v77
	s_waitcnt lgkmcnt(0)
	v_pk_add_f32 v[80:81], v[64:65], v[128:129]
	v_mul_f32_e32 v64, v69, v69
	v_pk_add_f32 v[78:79], v[78:79], v[142:143]
	v_fmac_f32_e32 v84, v76, v76
	v_pk_add_f32 v[70:71], v[70:71], v[134:135]
	v_fmac_f32_e32 v64, v68, v68
	v_fmac_f32_e32 v84, v78, v78
	v_fmac_f32_e32 v64, v70, v70
	v_pk_add_f32 v[72:73], v[72:73], v[136:137]
	v_fmac_f32_e32 v84, v79, v79
	v_fmac_f32_e32 v64, v71, v71
	v_fmac_f32_e32 v84, v72, v72
	v_fmac_f32_e32 v64, v80, v80
	v_pk_add_f32 v[74:75], v[74:75], v[138:139]
	v_fmac_f32_e32 v84, v73, v73
	v_pk_add_f32 v[82:83], v[66:67], v[130:131]
	v_fmac_f32_e32 v64, v81, v81
	v_fmac_f32_e32 v84, v74, v74
	v_fmac_f32_e32 v64, v82, v82
	v_fmac_f32_e32 v84, v75, v75
	v_fmac_f32_e32 v64, v83, v83
	v_add_f32_e32 v84, v84, v64
	ds_bpermute_b32 v85, v218, v84
	v_lshl_add_u64 v[64:65], s[30:31], 0, v[202:203]
	v_lshl_add_u64 v[66:67], v[194:195], 2, v[64:65]
	global_store_dwordx4 v[66:67], v[76:79], off
	global_store_dwordx4 v[66:67], v[72:75], off offset:16
	global_store_dwordx4 v[66:67], v[68:71], off offset:512
	global_store_dwordx4 v[66:67], v[80:83], off offset:528
	s_waitcnt lgkmcnt(0)
	v_add_f32_e32 v64, v84, v85
	ds_bpermute_b32 v65, v126, v64
	s_and_saveexec_b64 s[0:1], vcc
	s_cbranch_execz .LBB0_775
	s_waitcnt lgkmcnt(0)
	v_add_f32_e32 v66, v64, v65
	v_lshl_add_u64 v[64:65], v[200:201], 2, s[38:39]
	global_atomic_add_f32 v[64:65], v66, off
